# merge: gate GEMM prologue stage loads issued early (after previous GEMM, before br_store / gate_reg), prologue only waits
# baseline (speedup 1.0000x reference)
; DI unsigned pack2(float a, float b) { unsigned r; asm("v_cvt_pk_bf16_f32 %0, %1, %2\n\ts_nop 1" : "=v"(r) : "v"(a), "v"(b)); return r; }
; DI void lds_barrier() { asm volatile("s_waitcnt lgkmcnt(0)\n\ts_barrier" ::: "memory"); }
; DI int tid512() { int t = threadIdx.x; asm volatile("" : "+v"(t)); return t; }
; #define G_WAIT_V(n) asm volatile("s_waitcnt vmcnt(" #n ")" ::: "memory")
; #define G_BAR __builtin_amdgcn_s_barrier()
; DI u32x4* merge_scratch(PREF p, int region) { const int t = tid512(); return (u32x4*)p.fbuf + (size_t)blockIdx.x * 40960 + region * 8192 + (t >> 6) * 1024 + (t & 63); }
;     ...
;   const int t = tid512();
;   const int wid = t >> 6, lane = t & 63, wr = wid >> 2, wc = wid & 3, fr = lane & 15, fq = lane >> 4;
;   int r0, c0, r1, c1;
;   g_stage_rc(t * 16, r0, c0); g_stage_rc(t * 16 + 8192, r1, c1);
;   const int oa0 = r0 * LDA + c0, oa1 = r1 * LDA + c1, ob0 = r0 * LDB + c0, ob1 = r1 * LDB + c1;
;   const int obr = fr * 64 + fq * 16, rdo = obr ^ (((obr >> 9) & 1) << 5);
;   bf16x8 At[4][2], B0[2][2], B1[2][2];
;   constexpr int nt = K / 64;
;   lds_barrier();
;   G_STAGE(G_SB(0, 0), B, ob0, ob1, LDB, 0, KB(0)); G_STAGE(G_SA(0, 0), A, oa0, oa1, LDA, 0, KA(0));
;   G_STAGE(G_SB(0, 1), B, ob0, ob1, LDB, 128, KB(0)); G_STAGE(G_SA(0, 1), A, oa0, oa1, LDA, 128, KA(0));
;   if (wr == 1) G_BAR;
;   G_WAIT_V(4); G_BAR;
;   G_STAGE(G_SB(1, 0), B, ob0, ob1, LDB, 0, KB(1)); G_STAGE(G_SA(1, 0), A, oa0, oa1, LDA, 0, KA(1)); G_STAGE(G_SB(1, 1), B, ob0, ob1, LDB, 128, KB(1));
;   G_WAIT_V(6); G_BAR;
; DI void br_store(PREF p, const f32x4 (&acc)[2][2][4][2], int slot) {
;   u32x4* sb = merge_scratch(p, slot);
; #pragma unroll
;   for (int ai = 0; ai < 2; ++ai)
; #pragma unroll
;     for (int bj = 0; bj < 2; ++bj)
; #pragma unroll
;       for (int m = 0; m < 4; ++m) {
;         u32x4 o;
;         o.x = pack2(acc[ai][bj][m][0][0], acc[ai][bj][m][0][1]); o.y = pack2(acc[ai][bj][m][0][2], acc[ai][bj][m][0][3]);
;         o.z = pack2(acc[ai][bj][m][1][0], acc[ai][bj][m][1][1]); o.w = pack2(acc[ai][bj][m][1][2], acc[ai][bj][m][1][3]);
;         sb[((ai * 2 + bj) * 4 + m) * 64] = o;
;       }
; }
.LBB0_100:
	s_or_b64 exec, exec, s[10:11]
	v_mov_b32_e32 v0, v168
	v_cvt_pk_bf16_f32 v102, v102, v103
	v_cvt_pk_bf16_f32 v103, v104, v105
	v_cvt_pk_bf16_f32 v105, v96, v97
	v_cvt_pk_bf16_f32 v96, v90, v91
	v_cvt_pk_bf16_f32 v97, v92, v93
	s_nop 0
	v_lshlrev_b32_e32 v130, 4, v0
	v_and_b32_e32 v130, 0xfffffc00, v130
	v_ashrrev_i32_e32 v131, 31, v130
	v_and_b32_e32 v0, 63, v0
	v_lshl_add_u64 v[130:131], v[130:131], 4, s[18:19]
	v_lshlrev_b32_e32 v0, 4, v0
	v_lshl_add_u64 v[130:131], v[130:131], 0, v[0:1]
	v_add_co_u32_e32 v90, vcc, s80, v130
	s_movk_i32 s0, 0x3000
	s_nop 0
	v_addc_co_u32_e32 v91, vcc, 0, v131, vcc
	v_add_co_u32_e32 v92, vcc, s40, v130
	v_cvt_pk_bf16_f32 v30, v30, v31
	v_cvt_pk_bf16_f32 v31, v32, v33
	v_cvt_pk_bf16_f32 v32, v26, v27
	s_mov_b32 s23, 0
	s_nop 0
	v_addc_co_u32_e32 v93, vcc, 0, v131, vcc
	v_add_co_u32_e32 v26, vcc, s0, v130
	s_mov_b64 s[0:1], s[14:15]
	s_add_u32 s26, s0, s8
	s_addc_u32 s27, s1, s9
	s_lshl_b32 s28, s22, 8
	s_ashr_i32 s29, s28, 31
	s_add_u32 s30, s26, 0x40000
	s_addc_u32 s31, s27, 0
	s_add_u32 s34, s26, 0x40780
	s_addc_u32 s35, s27, 0
	s_lshl_b64 s[0:1], s[28:29], 2
	s_add_u32 s25, s49, s0
	s_addc_u32 s48, s69, s1
	s_lshl_b32 s12, s24, 8
	s_lshl_b64 s[0:1], s[28:29], 1
	s_add_u32 s36, s16, s0
	s_addc_u32 s37, s17, s1
	s_or_b32 s13, s12, 0x80
	s_lshl_b64 s[0:1], s[28:29], 11
	s_add_u32 s40, s46, s0
	v_addc_co_u32_e32 v27, vcc, 0, v131, vcc
	s_addc_u32 s41, s47, s1
	s_add_u32 s8, s40, 0x580000
	s_addc_u32 s9, s41, 0
	v_and_b32_e32 v196, 63, v168
	v_lshrrev_b32_e32 v197, 6, v168
	v_lshrrev_b32_e32 v198, 1, v197
	v_lshrrev_b32_e32 v199, 2, v196
	v_lshl_add_u32 v198, v198, 4, v199
	v_and_b32_e32 v199, 1, v197
	v_and_b32_e32 v200, 3, v196
	v_lshlrev_b32_e32 v200, 3, v200
	v_lshl_add_u32 v199, v199, 5, v200
	v_bfe_u32 v201, v168, 5, 1
	v_lshlrev_b32_e32 v201, 4, v201
	v_xor_b32_e32 v199, v199, v201
	v_lshlrev_b32_e32 v198, 11, v198
	v_lshl_add_u32 v182, v199, 1, v198
	v_mov_b32_e32 v183, 0
	v_add_u32_e32 v184, 0x20000, v182
	v_mov_b32_e32 v185, 0
	v_readfirstlane_b32 s0, v168
	s_lshl_b32 s0, s0, 4
	s_mov_b64 s[98:99], 0x40000
	v_lshl_add_u64 v[186:187], s[8:9], 0, v[182:183]
	v_lshl_add_u64 v[188:189], s[8:9], 0, v[184:185]
	v_lshl_add_u64 v[190:191], s[26:27], 0, v[182:183]
	v_lshl_add_u64 v[192:193], s[26:27], 0, v[184:185]
	s_add_u32 m0, s0, 0x10000
	s_nop 0
	global_load_lds_dwordx4 v[186:187], off
	s_add_u32 m0, s0, 0x12000
	s_nop 0
	global_load_lds_dwordx4 v[188:189], off
	s_mov_b32 m0, s0
	s_nop 0
	global_load_lds_dwordx4 v[190:191], off
	s_add_u32 m0, s0, 0x2000
	s_nop 0
	global_load_lds_dwordx4 v[192:193], off
	s_add_u32 m0, s0, 0x14000
	v_lshl_add_u64 v[194:195], v[186:187], 0, s[98:99]
	global_load_lds_dwordx4 v[194:195], off
	s_add_u32 m0, s0, 0x16000
	v_lshl_add_u64 v[196:197], v[188:189], 0, s[98:99]
	global_load_lds_dwordx4 v[196:197], off
	s_add_u32 m0, s0, 0x4000
	v_lshl_add_u64 v[194:195], v[190:191], 0, s[98:99]
	global_load_lds_dwordx4 v[194:195], off
	s_add_u32 m0, s0, 0x6000
	v_lshl_add_u64 v[196:197], v[192:193], 0, s[98:99]
	global_load_lds_dwordx4 v[196:197], off
	s_add_u32 m0, s0, 0x18000
	v_lshl_add_u64 v[194:195], v[186:187], 0, s[76:77]
	global_load_lds_dwordx4 v[194:195], off
	s_add_u32 m0, s0, 0x1a000
	v_lshl_add_u64 v[196:197], v[188:189], 0, s[76:77]
	global_load_lds_dwordx4 v[196:197], off
	s_add_u32 m0, s0, 0x8000
	v_lshl_add_u64 v[194:195], v[190:191], 0, s[76:77]
	global_load_lds_dwordx4 v[194:195], off
	s_add_u32 m0, s0, 0xa000
	v_lshl_add_u64 v[196:197], v[192:193], 0, s[76:77]
	global_load_lds_dwordx4 v[196:197], off
	s_add_u32 m0, s0, 0x1c000
	v_lshl_add_u64 v[194:195], v[186:187], 0, s[78:79]
	global_load_lds_dwordx4 v[194:195], off
	s_add_u32 m0, s0, 0x1e000
	v_lshl_add_u64 v[196:197], v[188:189], 0, s[78:79]
	global_load_lds_dwordx4 v[196:197], off
	v_cvt_pk_bf16_f32 v126, v126, v127
	v_cvt_pk_bf16_f32 v127, v128, v129
	v_cvt_pk_bf16_f32 v128, v122, v123
	v_cvt_pk_bf16_f32 v129, v124, v125
	global_store_dwordx4 v[130:131], v[126:129], off
	v_cvt_pk_bf16_f32 v118, v118, v119
	v_cvt_pk_bf16_f32 v119, v120, v121
	v_cvt_pk_bf16_f32 v120, v114, v115
	v_cvt_pk_bf16_f32 v121, v116, v117
	global_store_dwordx4 v[130:131], v[118:121], off offset:1024
	v_cvt_pk_bf16_f32 v110, v110, v111
	v_cvt_pk_bf16_f32 v111, v112, v113
	v_cvt_pk_bf16_f32 v112, v106, v107
	v_cvt_pk_bf16_f32 v113, v108, v109
	global_store_dwordx4 v[130:131], v[110:113], off offset:2048
	v_cvt_pk_bf16_f32 v104, v94, v95
	global_store_dwordx4 v[130:131], v[102:105], off offset:3072
	v_cvt_pk_bf16_f32 v94, v98, v99
	v_cvt_pk_bf16_f32 v95, v100, v101
	global_store_dwordx4 v[92:93], v[94:97], off offset:-4096
	v_cvt_pk_bf16_f32 v86, v86, v87
	v_cvt_pk_bf16_f32 v87, v88, v89
	v_cvt_pk_bf16_f32 v88, v82, v83
	v_cvt_pk_bf16_f32 v89, v84, v85
	global_store_dwordx4 v[90:91], v[86:89], off offset:1024
	v_cvt_pk_bf16_f32 v78, v78, v79
	v_cvt_pk_bf16_f32 v79, v80, v81
	v_cvt_pk_bf16_f32 v80, v74, v75
	v_cvt_pk_bf16_f32 v81, v76, v77
	global_store_dwordx4 v[90:91], v[78:81], off offset:2048
	v_cvt_pk_bf16_f32 v66, v66, v67
	v_cvt_pk_bf16_f32 v67, v68, v69
	v_cvt_pk_bf16_f32 v68, v58, v59
	v_cvt_pk_bf16_f32 v69, v60, v61
	global_store_dwordx4 v[90:91], v[66:69], off offset:3072
	v_cvt_pk_bf16_f32 v58, v70, v71
	v_cvt_pk_bf16_f32 v59, v72, v73
	v_cvt_pk_bf16_f32 v60, v62, v63
	v_cvt_pk_bf16_f32 v61, v64, v65
	global_store_dwordx4 v[92:93], v[58:61], off
	v_cvt_pk_bf16_f32 v54, v54, v55
	v_cvt_pk_bf16_f32 v55, v56, v57
	v_cvt_pk_bf16_f32 v56, v50, v51
	v_cvt_pk_bf16_f32 v57, v52, v53
	global_store_dwordx4 v[92:93], v[54:57], off offset:1024
	v_cvt_pk_bf16_f32 v46, v46, v47
	v_cvt_pk_bf16_f32 v47, v48, v49
	v_cvt_pk_bf16_f32 v48, v42, v43
	v_cvt_pk_bf16_f32 v49, v44, v45
	global_store_dwordx4 v[92:93], v[46:49], off offset:2048
	v_cvt_pk_bf16_f32 v38, v38, v39
	v_cvt_pk_bf16_f32 v39, v40, v41
	v_cvt_pk_bf16_f32 v40, v34, v35
	v_cvt_pk_bf16_f32 v41, v36, v37
	global_store_dwordx4 v[92:93], v[38:41], off offset:3072
	v_cvt_pk_bf16_f32 v33, v28, v29
	global_store_dwordx4 v[26:27], v[30:33], off
	v_cvt_pk_bf16_f32 v22, v22, v23
	v_cvt_pk_bf16_f32 v23, v24, v25
	v_cvt_pk_bf16_f32 v24, v18, v19
	v_cvt_pk_bf16_f32 v25, v20, v21
	global_store_dwordx4 v[26:27], v[22:25], off offset:1024
	v_cvt_pk_bf16_f32 v14, v14, v15
	v_cvt_pk_bf16_f32 v15, v16, v17
	v_cvt_pk_bf16_f32 v16, v10, v11
	v_cvt_pk_bf16_f32 v17, v12, v13
	global_store_dwordx4 v[26:27], v[14:17], off offset:2048
	v_cvt_pk_bf16_f32 v6, v6, v7
	v_cvt_pk_bf16_f32 v7, v8, v9
	v_cvt_pk_bf16_f32 v8, v2, v3
	v_cvt_pk_bf16_f32 v9, v4, v5
	global_store_dwordx4 v[26:27], v[6:9], off offset:3072
	s_branch .LBB0_102

; DI void lds_barrier() { asm volatile("s_waitcnt lgkmcnt(0)\n\ts_barrier" ::: "memory"); }
; DI int tid512() { int t = threadIdx.x; asm volatile("" : "+v"(t)); return t; }
; #define G_BAR __builtin_amdgcn_s_barrier()
;     ...
;   const int t = tid512();
;   const int wid = t >> 6, lane = t & 63, wr = wid >> 2, wc = wid & 3, fr = lane & 15, fq = lane >> 4;
;   int r0, c0, r1, c1;
;   g_stage_rc(t * 16, r0, c0); g_stage_rc(t * 16 + 8192, r1, c1);
;   const int oa0 = r0 * LDA + c0, oa1 = r1 * LDA + c1, ob0 = r0 * LDB + c0, ob1 = r1 * LDB + c1;
;   const int obr = fr * 64 + fq * 16, rdo = obr ^ (((obr >> 9) & 1) << 5);
;   bf16x8 At[4][2], B0[2][2], B1[2][2];
;   constexpr int nt = K / 64;
;   lds_barrier();
;   G_STAGE(G_SB(0, 0), B, ob0, ob1, LDB, 0, KB(0)); G_STAGE(G_SA(0, 0), A, oa0, oa1, LDA, 0, KA(0));
;   G_STAGE(G_SB(0, 1), B, ob0, ob1, LDB, 128, KB(0)); G_STAGE(G_SA(0, 1), A, oa0, oa1, LDA, 128, KA(0));
;   if (wr == 1) G_BAR;
.LBB0_102:
	s_lshl_b32 s52, s23, 10
	s_add_u32 s0, s52, s28
	v_mov_b32_e32 v0, v168
	s_addc_u32 s1, 0, s29
	s_lshl_b64 s[0:1], s[0:1], 11
	v_lshlrev_b32_e32 v143, 4, v0
	v_and_b32_e32 v2, 32, v0
	v_lshrrev_b32_e32 v4, 1, v0
	v_bitop3_b32 v2, v143, v2, 48 bitop3:0x6c
	s_add_u32 s8, s65, s0
	v_ashrrev_i32_e32 v10, 3, v0
	v_bfe_u32 v13, v0, 2, 4
	s_mov_b32 s0, 0x3ffff0
	v_and_b32_e32 v11, 32, v4
	v_lshrrev_b32_e32 v12, 1, v2
	v_add_u32_e32 v144, 0x2000, v143
	v_and_or_b32 v3, v10, s0, v13
	v_or_b32_e32 v2, v12, v11
	v_ashrrev_i32_e32 v15, 7, v144
	v_and_or_b32 v4, v15, s0, v13
	v_lshl_or_b32 v132, v3, 10, v2
	v_lshl_or_b32 v130, v4, 10, v2
	v_ashrrev_i32_e32 v133, 31, v132
	v_add_u32_e32 v146, 0x10000, v143
	s_addc_u32 s9, s68, s1
	v_lshlrev_b64 v[16:17], 1, v[132:133]
	v_readfirstlane_b32 s0, v146
	v_ashrrev_i32_e32 v131, 31, v130
	v_add_u32_e32 v147, 0x12000, v143
	s_waitcnt lgkmcnt(0)
	s_barrier
	v_lshl_add_u64 v[2:3], s[8:9], 0, v[16:17]
	s_mov_b32 m0, s0
	v_lshlrev_b64 v[18:19], 1, v[130:131]
	v_readfirstlane_b32 s0, v147
	v_lshl_add_u64 v[6:7], s[8:9], 0, v[18:19]
	s_mov_b32 m0, s0
	v_readfirstlane_b32 s0, v143
	v_lshl_add_u64 v[8:9], s[26:27], 0, v[16:17]
	s_mov_b32 m0, s0
	v_readfirstlane_b32 s0, v144
	s_mov_b32 m0, s0
	s_add_u32 s0, s8, 0x40000
	v_add_u32_e32 v149, 0x14000, v143
	v_lshl_add_u64 v[4:5], s[26:27], 0, v[18:19]
	s_addc_u32 s1, s9, 0
	v_readfirstlane_b32 s10, v149
	v_lshl_add_u64 v[20:21], s[0:1], 0, v[16:17]
	s_mov_b32 m0, s10
	v_add_u32_e32 v150, 0x16000, v143
	v_lshl_add_u64 v[20:21], s[0:1], 0, v[18:19]
	v_readfirstlane_b32 s0, v150
	v_add_u32_e32 v151, 0x4000, v143
	s_mov_b32 m0, s0
	v_readfirstlane_b32 s0, v151
	v_add_u32_e32 v152, 0x6000, v143
	v_lshl_add_u64 v[16:17], s[30:31], 0, v[16:17]
	s_mov_b32 m0, s0
	v_readfirstlane_b32 s0, v152
	v_lshl_add_u64 v[16:17], s[30:31], 0, v[18:19]
	s_mov_b32 m0, s0
	v_ashrrev_i32_e32 v14, 8, v0
	v_cmp_eq_u32_e32 vcc, 1, v14
	s_and_saveexec_b64 s[10:11], vcc
	s_cbranch_execz .LBB0_104
	s_barrier
; #define G_WAIT_V(n) asm volatile("s_waitcnt vmcnt(" #n ")" ::: "memory")
; #define G_BAR __builtin_amdgcn_s_barrier()
;     ...
;   G_WAIT_V(4); G_BAR;
;   G_STAGE(G_SB(1, 0), B, ob0, ob1, LDB, 0, KB(1)); G_STAGE(G_SA(1, 0), A, oa0, oa1, LDA, 0, KA(1)); G_STAGE(G_SB(1, 1), B, ob0, ob1, LDB, 128, KB(1));
;   G_WAIT_V(6); G_BAR;
; DI void zero_acc256(f32x4 (&a)[2][2][4][2]) {
; #pragma unroll
;   for (int i = 0; i < 2; ++i)
; #pragma unroll
;     for (int j = 0; j < 2; ++j)
; #pragma unroll
;       for (int m = 0; m < 4; ++m)
; #pragma unroll
;         for (int n = 0; n < 2; ++n)
; #pragma unroll
;           for (int e = 0; e < 4; ++e) a[i][j][m][n][e] = 0.f;
; }
.LBB0_104:
	s_or_b64 exec, exec, s[10:11]
	v_add_u32_e32 v153, 0x18000, v143
	v_add_u32_e32 v154, 0x1a000, v143
	v_readfirstlane_b32 s0, v153
	v_lshl_add_u64 v[2:3], v[2:3], 0, s[76:77]
	s_mov_b32 m0, s0
	v_readfirstlane_b32 s0, v154
	v_add_u32_e32 v155, 0x8000, v143
	s_waitcnt vmcnt(0)
	s_barrier
	v_lshl_add_u64 v[2:3], v[6:7], 0, s[76:77]
	s_mov_b32 m0, s0
	v_readfirstlane_b32 s0, v155
	v_add_u32_e32 v156, 0xa000, v143
	v_lshl_add_u64 v[2:3], v[8:9], 0, s[76:77]
	s_mov_b32 m0, s0
	v_readfirstlane_b32 s0, v156
	s_mov_b32 m0, s0
	s_add_u32 s0, s8, 0x40080
	v_add_u32_e32 v157, 0x1c000, v143
	v_lshl_add_u64 v[2:3], v[4:5], 0, s[76:77]
	s_addc_u32 s1, s9, 0
	v_readfirstlane_b32 s8, v157
	v_lshl_add_u64 v[2:3], v[132:133], 1, s[0:1]
	s_mov_b32 m0, s8
	v_add_u32_e32 v159, 0x1e000, v143
	v_lshl_add_u64 v[2:3], v[130:131], 1, s[0:1]
	v_readfirstlane_b32 s0, v159
	s_mov_b32 m0, s0
	v_lshlrev_b32_e32 v17, 6, v0
	v_lshlrev_b32_e32 v2, 10, v15
	v_and_b32_e32 v2, 0xffffc000, v2
	v_lshlrev_b32_e32 v4, 10, v13
	v_lshlrev_b32_e32 v5, 10, v10
	v_and_b32_e32 v16, 48, v0
	v_and_b32_e32 v18, 0x3c0, v17
	v_lshlrev_b32_e32 v20, 2, v0
	v_or3_b32 v2, v12, v2, v4
	v_and_b32_e32 v5, 0xffffc000, v5
	v_or_b32_e32 v19, v18, v16
	v_and_b32_e32 v20, 32, v20
	s_mov_b32 s0, 0x14000
	v_add_u32_e32 v2, v2, v11
	v_or3_b32 v4, v12, v5, v4
	v_bitop3_b32 v8, v19, s0, v20 bitop3:0xde
	s_mov_b32 s0, 0x18000
	v_ashrrev_i32_e32 v3, 31, v2
	v_add_u32_e32 v4, v4, v11
	s_waitcnt vmcnt(6)
	v_bitop3_b32 v9, v19, s0, v20 bitop3:0xde
	s_mov_b32 s0, 0x1c000
	v_lshlrev_b64 v[2:3], 1, v[2:3]
	v_ashrrev_i32_e32 v5, 31, v4
	v_bitop3_b32 v16, v18, v20, v16 bitop3:0x36
	v_bitop3_b32 v6, v19, s88, v20 bitop3:0xde
	v_lshlrev_b32_e32 v7, 13, v14
	v_bitop3_b32 v14, v19, s0, v20 bitop3:0xde
	v_and_b32_e32 v17, 0x3000, v17
	v_lshl_add_u64 v[134:135], s[26:27], 0, v[2:3]
	v_lshlrev_b64 v[4:5], 1, v[4:5]
	v_lshl_add_u64 v[138:139], s[40:41], 0, v[2:3]
	v_mov_b32_e32 v2, 0
	v_lshl_add_u64 v[136:137], s[26:27], 0, v[4:5]
	v_lshl_add_u64 v[140:141], s[40:41], 0, v[4:5]
	s_mov_b32 s10, -2
	s_mov_b64 s[8:9], 0
	v_add_u32_e32 v160, v6, v17
	v_add_u32_e32 v142, v16, v7
	v_add_u32_e32 v158, v8, v17
	v_add_u32_e32 v148, v9, v17
	v_add_u32_e32 v145, v14, v17
	v_mov_b32_e32 v3, v2
	v_mov_b32_e32 v4, v2
	v_mov_b32_e32 v5, v2
	v_mov_b32_e32 v6, v2
	v_mov_b32_e32 v7, v2
	v_mov_b32_e32 v8, v2
	v_mov_b32_e32 v9, v2
	v_mov_b32_e32 v10, v2
	v_mov_b32_e32 v11, v2
	v_mov_b32_e32 v12, v2
	v_mov_b32_e32 v13, v2
	v_mov_b32_e32 v14, v2
	v_mov_b32_e32 v15, v2
	v_mov_b32_e32 v16, v2
	v_mov_b32_e32 v17, v2
	v_mov_b32_e32 v18, v2
	v_mov_b32_e32 v19, v2
	v_mov_b32_e32 v20, v2
	v_mov_b32_e32 v21, v2
	v_mov_b32_e32 v22, v2
	v_mov_b32_e32 v23, v2
	v_mov_b32_e32 v24, v2
	v_mov_b32_e32 v25, v2
	v_mov_b32_e32 v26, v2
	v_mov_b32_e32 v27, v2
	v_mov_b32_e32 v28, v2
	v_mov_b32_e32 v29, v2
	v_mov_b32_e32 v30, v2
	v_mov_b32_e32 v31, v2
	v_mov_b32_e32 v32, v2
	v_mov_b32_e32 v33, v2
	v_mov_b32_e32 v34, v2
	v_mov_b32_e32 v35, v2
	v_mov_b32_e32 v36, v2
	v_mov_b32_e32 v37, v2
	v_mov_b32_e32 v38, v2
	v_mov_b32_e32 v39, v2
	v_mov_b32_e32 v40, v2
	v_mov_b32_e32 v41, v2
	v_mov_b32_e32 v42, v2
	v_mov_b32_e32 v43, v2
	v_mov_b32_e32 v44, v2
	v_mov_b32_e32 v45, v2
	v_mov_b32_e32 v46, v2
	v_mov_b32_e32 v47, v2
	v_mov_b32_e32 v48, v2
	v_mov_b32_e32 v49, v2
	v_mov_b32_e32 v50, v2
	v_mov_b32_e32 v51, v2
	v_mov_b32_e32 v52, v2
	v_mov_b32_e32 v53, v2
	v_mov_b32_e32 v54, v2
	v_mov_b32_e32 v55, v2
	v_mov_b32_e32 v56, v2
	v_mov_b32_e32 v57, v2
	v_mov_b32_e32 v58, v2
	v_mov_b32_e32 v59, v2
	v_mov_b32_e32 v60, v2
	v_mov_b32_e32 v61, v2
	v_mov_b32_e32 v62, v2
	v_mov_b32_e32 v63, v2
	v_mov_b32_e32 v64, v2
	v_mov_b32_e32 v65, v2
	v_mov_b32_e32 v66, v2
	v_mov_b32_e32 v67, v2
	v_mov_b32_e32 v68, v2
	v_mov_b32_e32 v69, v2
	v_mov_b32_e32 v70, v2
	v_mov_b32_e32 v71, v2
	v_mov_b32_e32 v72, v2
	v_mov_b32_e32 v73, v2
	v_mov_b32_e32 v74, v2
	v_mov_b32_e32 v75, v2
	v_mov_b32_e32 v76, v2
	v_mov_b32_e32 v77, v2
	v_mov_b32_e32 v78, v2
	v_mov_b32_e32 v79, v2
	v_mov_b32_e32 v80, v2
	v_mov_b32_e32 v81, v2
	v_mov_b32_e32 v82, v2
	v_mov_b32_e32 v83, v2
	v_mov_b32_e32 v84, v2
	v_mov_b32_e32 v85, v2
	v_mov_b32_e32 v86, v2
	v_mov_b32_e32 v87, v2
	v_mov_b32_e32 v88, v2
	v_mov_b32_e32 v89, v2
	v_mov_b32_e32 v90, v2
	v_mov_b32_e32 v91, v2
	v_mov_b32_e32 v92, v2
	v_mov_b32_e32 v93, v2
	v_mov_b32_e32 v94, v2
	v_mov_b32_e32 v95, v2
	v_mov_b32_e32 v96, v2
	v_mov_b32_e32 v97, v2
	v_mov_b32_e32 v98, v2
	v_mov_b32_e32 v99, v2
	v_mov_b32_e32 v100, v2
	v_mov_b32_e32 v101, v2
	v_mov_b32_e32 v102, v2
	v_mov_b32_e32 v103, v2
	v_mov_b32_e32 v104, v2
	v_mov_b32_e32 v105, v2
	v_mov_b32_e32 v106, v2
	v_mov_b32_e32 v107, v2
	v_mov_b32_e32 v108, v2
	v_mov_b32_e32 v109, v2
	v_mov_b32_e32 v110, v2
	v_mov_b32_e32 v111, v2
	v_mov_b32_e32 v112, v2
	v_mov_b32_e32 v113, v2
	v_mov_b32_e32 v114, v2
	v_mov_b32_e32 v115, v2
	v_mov_b32_e32 v116, v2
	v_mov_b32_e32 v117, v2
	v_mov_b32_e32 v118, v2
	v_mov_b32_e32 v119, v2
	v_mov_b32_e32 v120, v2
	v_mov_b32_e32 v121, v2
	v_mov_b32_e32 v122, v2
	v_mov_b32_e32 v123, v2
	v_mov_b32_e32 v124, v2
	v_mov_b32_e32 v125, v2
	v_mov_b32_e32 v126, v2
	v_mov_b32_e32 v127, v2
	v_mov_b32_e32 v128, v2
	v_mov_b32_e32 v129, v2
	s_barrier

; DI int tid512() { int t = threadIdx.x; asm volatile("" : "+v"(t)); return t; }
; #define G_WAIT_V(n) asm volatile("s_waitcnt vmcnt(" #n ")" ::: "memory")
; #define G_BAR __builtin_amdgcn_s_barrier()
; DI u32x4* merge_scratch(PREF p, int region) { const int t = tid512(); return (u32x4*)p.fbuf + (size_t)blockIdx.x * 40960 + region * 8192 + (t >> 6) * 1024 + (t & 63); }
;     ...
;   G_STAGE(G_SB(0, 0), B, ob0, ob1, LDB, 0, KB(0)); G_STAGE(G_SA(0, 0), A, oa0, oa1, LDA, 0, KA(0));
;   G_STAGE(G_SB(0, 1), B, ob0, ob1, LDB, 128, KB(0)); G_STAGE(G_SA(0, 1), A, oa0, oa1, LDA, 128, KA(0));
;   if (wr == 1) G_BAR;
;   G_WAIT_V(4); G_BAR;
;   G_STAGE(G_SB(1, 0), B, ob0, ob1, LDB, 0, KB(1)); G_STAGE(G_SA(1, 0), A, oa0, oa1, LDA, 0, KA(1)); G_STAGE(G_SB(1, 1), B, ob0, ob1, LDB, 128, KB(1));
; DI void gate_reg(PREF p, int l, int n, f32x4 (&acc)[2][2][4][2], int dt) {
;   const u32x4* sbn = merge_scratch(p, n);
;   u32x4* ssum = merge_scratch(p, 4);
;   const int t = tid512(), wid = t >> 6, lane = t & 63, wc = wid & 3, fr = lane & 15;
;   const float* bm = p.b_merge + (size_t)l * 4096 + n * 1024 + dt * 256 + wc * 32 + fr;
;   float bias[2][2];
; #pragma unroll
;   for (int bj = 0; bj < 2; ++bj)
; #pragma unroll
;     for (int nn = 0; nn < 2; ++nn) bias[bj][nn] = bm[bj * 128 + nn * 16];
; #pragma unroll
;   for (int ai = 0; ai < 2; ++ai)
; #pragma unroll
;     for (int bj = 0; bj < 2; ++bj) {
;       __builtin_amdgcn_sched_barrier(0);
;       u32x4 bn[4], pv[4];
; #pragma unroll
;       for (int m = 0; m < 4; ++m) {
;         bn[m] = sbn[((ai * 2 + bj) * 4 + m) * 64];
;         if (n > 0) pv[m] = ssum[((ai * 2 + bj) * 4 + m) * 64];
;       }
.LBB0_108:
	s_or_b64 exec, exec, s[8:9]
	s_cmp_eq_u32 s23, 3
	s_cbranch_scc1 .Lmy_pf_skip
	s_add_u32 s8, s40, 0x780000
	s_addc_u32 s9, s41, 0
	v_and_b32_e32 v196, 63, v168
	v_lshrrev_b32_e32 v197, 6, v168
	v_lshrrev_b32_e32 v198, 1, v197
	v_lshrrev_b32_e32 v199, 2, v196
	v_lshl_add_u32 v198, v198, 4, v199
	v_and_b32_e32 v199, 1, v197
	v_and_b32_e32 v200, 3, v196
	v_lshlrev_b32_e32 v200, 3, v200
	v_lshl_add_u32 v199, v199, 5, v200
	v_bfe_u32 v201, v168, 5, 1
	v_lshlrev_b32_e32 v201, 4, v201
	v_xor_b32_e32 v199, v199, v201
	v_lshlrev_b32_e32 v198, 11, v198
	v_lshl_add_u32 v182, v199, 1, v198
	v_mov_b32_e32 v183, 0
	v_add_u32_e32 v184, 0x20000, v182
	v_mov_b32_e32 v185, 0
	v_readfirstlane_b32 s0, v168
	s_lshl_b32 s0, s0, 4
	s_mov_b64 s[98:99], 0x40000
	v_lshl_add_u64 v[186:187], s[8:9], 0, v[182:183]
	v_lshl_add_u64 v[188:189], s[8:9], 0, v[184:185]
	v_lshl_add_u64 v[190:191], s[26:27], 0, v[182:183]
	v_lshl_add_u64 v[192:193], s[26:27], 0, v[184:185]
	s_add_u32 m0, s0, 0x10000
	s_nop 0
	global_load_lds_dwordx4 v[186:187], off
	s_add_u32 m0, s0, 0x12000
	s_nop 0
	global_load_lds_dwordx4 v[188:189], off
	s_mov_b32 m0, s0
	s_nop 0
	global_load_lds_dwordx4 v[190:191], off
	s_add_u32 m0, s0, 0x2000
	s_nop 0
	global_load_lds_dwordx4 v[192:193], off
	s_add_u32 m0, s0, 0x14000
	v_lshl_add_u64 v[194:195], v[186:187], 0, s[98:99]
	global_load_lds_dwordx4 v[194:195], off
	s_add_u32 m0, s0, 0x16000
	v_lshl_add_u64 v[196:197], v[188:189], 0, s[98:99]
	global_load_lds_dwordx4 v[196:197], off
	s_add_u32 m0, s0, 0x4000
	v_lshl_add_u64 v[194:195], v[190:191], 0, s[98:99]
	global_load_lds_dwordx4 v[194:195], off
	s_add_u32 m0, s0, 0x6000
	v_lshl_add_u64 v[196:197], v[192:193], 0, s[98:99]
	global_load_lds_dwordx4 v[196:197], off
	s_add_u32 m0, s0, 0x18000
	v_lshl_add_u64 v[194:195], v[186:187], 0, s[76:77]
	global_load_lds_dwordx4 v[194:195], off
	s_add_u32 m0, s0, 0x1a000
	v_lshl_add_u64 v[196:197], v[188:189], 0, s[76:77]
	global_load_lds_dwordx4 v[196:197], off
	s_add_u32 m0, s0, 0x8000
	v_lshl_add_u64 v[194:195], v[190:191], 0, s[76:77]
	global_load_lds_dwordx4 v[194:195], off
	s_add_u32 m0, s0, 0xa000
	v_lshl_add_u64 v[196:197], v[192:193], 0, s[76:77]
	global_load_lds_dwordx4 v[196:197], off
	s_add_u32 m0, s0, 0x1c000
	v_lshl_add_u64 v[194:195], v[186:187], 0, s[78:79]
	global_load_lds_dwordx4 v[194:195], off
	s_add_u32 m0, s0, 0x1e000
	v_lshl_add_u64 v[196:197], v[188:189], 0, s[78:79]
	global_load_lds_dwordx4 v[196:197], off
.Lmy_pf_skip:
	v_mov_b32_e32 v8, v168
	v_mov_b32_e32 v18, v168
	v_mov_b32_e32 v0, v168
	s_lshl_b32 s0, s23, 13
	s_lshl_b64 s[8:9], s[52:53], 2
	v_and_b32_e32 v9, 15, v0
	s_add_u32 s8, s25, s8
	v_lshlrev_b32_e32 v0, 1, v0
	s_addc_u32 s9, s48, s9
	v_and_b32_e32 v0, 0x180, v0
	v_lshl_add_u64 v[6:7], s[8:9], 0, v[0:1]
	v_lshlrev_b32_e32 v0, 2, v9
	v_lshl_add_u64 v[6:7], v[6:7], 0, v[0:1]
	global_load_dword v184, v[6:7], off
	global_load_dword v183, v[6:7], off offset:64
	global_load_dword v182, v[6:7], off offset:512
	global_load_dword v162, v[6:7], off offset:576
	s_mov_b32 s1, s53
	v_lshlrev_b32_e32 v0, 4, v8
	s_lshl_b64 s[0:1], s[0:1], 4
	v_and_b32_e32 v6, 0xfffffc00, v0
	v_and_b32_e32 v0, 63, v8
	v_lshlrev_b32_e32 v8, 4, v18
	s_add_u32 s0, s63, s0
	v_ashrrev_i32_e32 v7, 31, v6
	v_and_b32_e32 v8, 0xfffffc00, v8
	s_addc_u32 s1, s64, s1
	v_ashrrev_i32_e32 v9, 31, v8
	v_and_b32_e32 v18, 63, v18
	v_lshl_add_u64 v[6:7], v[6:7], 4, s[0:1]
	v_lshlrev_b32_e32 v0, 4, v0
	v_lshl_add_u64 v[166:167], v[6:7], 0, v[0:1]
	v_lshl_add_u64 v[6:7], v[8:9], 4, s[20:21]
	v_lshlrev_b32_e32 v0, 4, v18
	s_cmp_lg_u32 s23, 0
	v_lshl_add_u64 v[164:165], v[6:7], 0, v[0:1]
	s_cselect_b64 s[10:11], -1, 0
	s_cmp_eq_u32 s23, 0
	global_load_dwordx4 v[154:157], v[166:167], off
	s_cbranch_scc1 .LBB0_110
	global_load_dwordx4 v[42:45], v[164:165], off
